# younger wave group's unit epilogue (critical path at unit boundaries) runs at raised wave priority; reset at loop entry and phase end
# speedup vs baseline: 1.0155x; 1.0001x over previous
; #define G_STAGE(bufoff, gbase, o0, h64) do { \
;         __builtin_amdgcn_global_load_lds((const unsigned*)((const char*)(gbase) + (o0)), (LAS unsigned*)(lds + (bufoff) + ldsw), 16, 0, 0); \
;         __builtin_amdgcn_global_load_lds((const unsigned*)((const char*)(gbase) + (h64) + (o0)), (LAS unsigned*)(lds + (bufoff) + ldsw + 8192), 16, 0, 0); } while (0)
; #define G_LDA(dst, b, h) do { _Pragma("unroll") for (int m = 0; m < 4; ++m) _Pragma("unroll") for (int k = 0; k < 2; ++k) dst[m][k] = *(const LAS bf16x8*)(lds + G_SA(b, h) + aoff + m * 2048 + k * 1024); } while (0)
; #define G_LDB(dst, b, h) do { _Pragma("unroll") for (int n = 0; n < 2; ++n) _Pragma("unroll") for (int k = 0; k < 2; ++k) dst[n][k] = *(const LAS bf16x8*)(lds + G_SB(b, h) + boff + n * 2048 + k * 1024); } while (0)
; #define G_SCHED __builtin_amdgcn_sched_barrier(0)
;     ...
;     for (;;) {
;         const bool has_next = sched_next<PH, SUB>(E.ws, E.layer, ui + 1, nxt, E.x);
;         if (!has_next) nxt = cur;
;         const char* nA = nxt.A; const char* nB = nxt.B;
; #pragma unroll 1
;         for (int t = 0; t < nt; t += 2) {
;             const bool last = (t == nt - 2);
;             const char* a1 = cA + (size_t)(t + 1) * ckA;
;             const char* a2 = last ? nA : cA + (size_t)(t + 2) * ckA; const char* b2 = last ? nB : cB + (size_t)(t + 2) * kB;
;             const char* a3 = a2 + ckA; const char* b3 = b2 + kB;
;             G_LDB(B0, 0, 0); G_SCHED; G_LDA(At, 0, 0); G_STAGE(G_SA(1, 1), a1 + chA, cA0, qA);
.LBB0_211:
	s_add_u32 s2, s2, 0x40080
	s_addc_u32 s3, s3, 0
	s_add_u32 s7, s22, 0x100
	s_addc_u32 s22, s23, 0
	s_mov_b32 s23, -2
	s_mov_b64 s[52:53], 0x40000
	s_mov_b64 s[54:55], 0x60000
	s_mov_b64 s[58:59], 0x20080
	s_mov_b64 s[62:63], 0x40080
	s_mov_b64 s[64:65], 0x60080
	s_cmp_eq_u32 s101, 2
	s_cselect_b32 s101, 0, s101
	s_setprio 0
	v_add_u32_e32 v255, 0x10000, v167
	s_add_u32 s4, s2, 0xfffc0080
	s_addc_u32 s5, s3, -1
	s_add_i32 s41, 0, 0x10000
	ds_read_b128 v[136:139], v255 offset:0
	ds_read_b128 v[144:147], v255 offset:1024
	ds_read_b128 v[148:151], v255 offset:2048
	ds_read_b128 v[152:155], v255 offset:3072
	s_cmp_eq_u32 s23, 12
	s_cselect_b32 s43, s19, s5
	s_cselect_b32 s42, s18, s4
	s_cselect_b32 s51, s21, s22
	s_cselect_b32 s50, s20, s7
	s_add_i32 m0, s27, 0xc000
	ds_read_b128 v[156:159], v172
	ds_read_b128 v[160:163], v172 offset:1024
	ds_read_b128 v[174:177], v172 offset:2048
	ds_read_b128 v[178:181], v172 offset:3072
	ds_read_b128 v[182:185], v172 offset:4096
	ds_read_b128 v[196:199], v172 offset:5120
	ds_read_b128 v[200:203], v172 offset:6144
	ds_read_b128 v[204:207], v172 offset:7168
	global_load_lds_dwordx4 v142, s[2:3]
	s_add_i32 m0, s27, 0xe000
	s_nop 0
	s_add_u32 vcc_lo, s2, s0
	s_addc_u32 vcc_hi, s3, s1
	global_load_lds_dwordx4 v142, vcc
	s_waitcnt lgkmcnt(8)
	s_cmp_eq_u32 s101, 1
	s_cbranch_scc1 .Ldb_WIN_skp
	s_barrier

;     ...
;         E.template run<cs.kind>(acc, cur, tid);
;         if (!has_next) break;
.Ldb_WIN_young:
	s_setprio 3
	s_mov_b32 s101, 2
	s_branch .Ldb_WIN_exit

; #define G_WAIT_V(n) asm volatile("s_waitcnt vmcnt(" #n ")" ::: "memory")
; #define G_BAR __builtin_amdgcn_s_barrier()
;     ...
;     G_WAIT_V(0);
;     if (wr == 0) G_BAR;
;     G_BAR;
.Ldbj_WIN_pe:
	s_setprio 0
	s_mov_b32 s101, 0
	s_waitcnt vmcnt(0)
	s_cmpk_gt_u32 s24, 0xff
	s_cbranch_scc1 .LBB0_343
	s_barrier

; #define G_STAGE(bufoff, gbase, o0, h64) do { \
;         __builtin_amdgcn_global_load_lds((const unsigned*)((const char*)(gbase) + (o0)), (LAS unsigned*)(lds + (bufoff) + ldsw), 16, 0, 0); \
;         __builtin_amdgcn_global_load_lds((const unsigned*)((const char*)(gbase) + (h64) + (o0)), (LAS unsigned*)(lds + (bufoff) + ldsw + 8192), 16, 0, 0); } while (0)
; #define G_LDA(dst, b, h) do { _Pragma("unroll") for (int m = 0; m < 4; ++m) _Pragma("unroll") for (int k = 0; k < 2; ++k) dst[m][k] = *(const LAS bf16x8*)(lds + G_SA(b, h) + aoff + m * 2048 + k * 1024); } while (0)
; #define G_LDB(dst, b, h) do { _Pragma("unroll") for (int n = 0; n < 2; ++n) _Pragma("unroll") for (int k = 0; k < 2; ++k) dst[n][k] = *(const LAS bf16x8*)(lds + G_SB(b, h) + boff + n * 2048 + k * 1024); } while (0)
; #define G_SCHED __builtin_amdgcn_sched_barrier(0)
;     ...
;     for (;;) {
;         const bool has_next = sched_next<PH, SUB>(E.ws, E.layer, ui + 1, nxt, E.x);
;         if (!has_next) nxt = cur;
;         const char* nA = nxt.A; const char* nB = nxt.B;
; #pragma unroll 1
;         for (int t = 0; t < nt; t += 2) {
;             const bool last = (t == nt - 2);
;             const char* a1 = cA + (size_t)(t + 1) * ckA;
;             const char* a2 = last ? nA : cA + (size_t)(t + 2) * ckA; const char* b2 = last ? nB : cB + (size_t)(t + 2) * kB;
;             const char* a3 = a2 + ckA; const char* b3 = b2 + kB;
;             G_LDB(B0, 0, 0); G_SCHED; G_LDA(At, 0, 0); G_STAGE(G_SA(1, 1), a1 + chA, cA0, qA);
.LBB0_449:
	s_add_u32 s6, s22, 0x20080
	s_addc_u32 s7, s23, 0
	s_add_u32 s19, s20, 0x100
	s_addc_u32 s20, s21, 0
	s_mov_b32 s21, -2
	s_mov_b64 s[50:51], 0x20080
	s_mov_b64 s[52:53], 0x10000
	s_mov_b64 s[54:55], 0x30000
	s_mov_b64 s[58:59], 0x10080
	s_mov_b64 s[62:63], 0x30080
	s_cmp_eq_u32 s101, 2
	s_cselect_b32 s101, 0, s101
	s_setprio 0
	v_add_u32_e32 v255, 0x10000, v145
	s_add_u32 s4, s6, 0xfffe0080
	s_addc_u32 s5, s7, -1
	s_add_i32 s41, 0, 0x10000
	ds_read_b128 v[140:143], v255 offset:0
	ds_read_b128 v[148:151], v255 offset:1024
	ds_read_b128 v[152:155], v255 offset:2048
	ds_read_b128 v[156:159], v255 offset:3072
	s_cmp_eq_u32 s21, 4
	s_cselect_b32 s23, s11, s5
	s_cselect_b32 s22, s10, s4
	s_cselect_b32 s43, s17, s20
	s_cselect_b32 s42, s16, s19
	s_add_i32 m0, s27, 0xc000
	ds_read_b128 v[160:163], v146
	ds_read_b128 v[164:167], v146 offset:1024
	ds_read_b128 v[172:175], v146 offset:2048
	ds_read_b128 v[176:179], v146 offset:3072
	ds_read_b128 v[180:183], v146 offset:4096
	ds_read_b128 v[196:199], v146 offset:5120
	ds_read_b128 v[200:203], v146 offset:6144
	ds_read_b128 v[204:207], v146 offset:7168
	global_load_lds_dwordx4 v138, s[6:7]
	s_add_i32 m0, s27, 0xe000
	s_nop 0
	s_add_u32 vcc_lo, s6, s52
	s_addc_u32 vcc_hi, s7, s53
	global_load_lds_dwordx4 v138, vcc
	s_waitcnt lgkmcnt(8)
	s_cmp_eq_u32 s101, 1
	s_cbranch_scc1 .Ldb_SSM1_skp
	s_barrier

;     ...
;     for (;;) {
;         const bool has_next = sched_next<PH, SUB>(E.ws, E.layer, ui + 1, nxt, E.x);
;         if (!has_next) nxt = cur;
;         const char* nA = nxt.A; const char* nB = nxt.B;
;     ...
;         if (!(cs.kind == K_MG_B && cur.aux < 2))
; #pragma unroll
;         for (int a = 0; a < 2; ++a)
; #pragma unroll
;             for (int b = 0; b < 2; ++b)
; #pragma unroll
;                 for (int m = 0; m < 4; ++m)
; #pragma unroll
;                     for (int n = 0; n < 2; ++n) acc[a][b][m][n] = (f32x4){0.f, 0.f, 0.f, 0.f};
.LBB0_741:
	v_mov_b64_e32 v[8:9], 0
	s_mov_b64 s[30:31], 0
	s_mov_b64 s[24:25], -1
	s_mov_b64 s[26:27], 0
	v_mov_b64_e32 v[10:11], 0
	v_mov_b64_e32 v[12:13], 0
	v_mov_b64_e32 v[14:15], 0
	v_mov_b64_e32 v[24:25], 0
	v_mov_b64_e32 v[26:27], 0
	v_mov_b64_e32 v[28:29], 0
	v_mov_b64_e32 v[30:31], 0
	v_mov_b64_e32 v[40:41], 0
	v_mov_b64_e32 v[42:43], 0
	v_mov_b64_e32 v[44:45], 0
	v_mov_b64_e32 v[46:47], 0
	v_mov_b64_e32 v[64:65], 0
	v_mov_b64_e32 v[66:67], 0
	v_mov_b64_e32 v[68:69], 0
	v_mov_b64_e32 v[70:71], 0
	v_mov_b64_e32 v[16:17], 0
	v_mov_b64_e32 v[18:19], 0
	v_mov_b64_e32 v[20:21], 0
	v_mov_b64_e32 v[22:23], 0
	v_mov_b64_e32 v[32:33], 0
	v_mov_b64_e32 v[34:35], 0
	v_mov_b64_e32 v[36:37], 0
	v_mov_b64_e32 v[38:39], 0
	v_mov_b64_e32 v[48:49], 0
	v_mov_b64_e32 v[50:51], 0
	v_mov_b64_e32 v[52:53], 0
	v_mov_b64_e32 v[54:55], 0
	v_mov_b64_e32 v[72:73], 0
	v_mov_b64_e32 v[74:75], 0
	v_mov_b64_e32 v[76:77], 0
	v_mov_b64_e32 v[78:79], 0
	v_mov_b64_e32 v[80:81], 0
	v_mov_b64_e32 v[82:83], 0
	v_mov_b64_e32 v[84:85], 0
	v_mov_b64_e32 v[86:87], 0
	v_mov_b64_e32 v[96:97], 0
	v_mov_b64_e32 v[98:99], 0
	v_mov_b64_e32 v[100:101], 0
	v_mov_b64_e32 v[102:103], 0
	v_mov_b64_e32 v[112:113], 0
	v_mov_b64_e32 v[114:115], 0
	v_mov_b64_e32 v[116:117], 0
	v_mov_b64_e32 v[118:119], 0
	v_mov_b64_e32 v[128:129], 0
	v_mov_b64_e32 v[130:131], 0
	v_mov_b64_e32 v[132:133], 0
	v_mov_b64_e32 v[134:135], 0
	v_mov_b64_e32 v[88:89], 0
	v_mov_b64_e32 v[90:91], 0
	v_mov_b64_e32 v[92:93], 0
	v_mov_b64_e32 v[94:95], 0
	v_mov_b64_e32 v[104:105], 0
	v_mov_b64_e32 v[106:107], 0
	v_mov_b64_e32 v[108:109], 0
	v_mov_b64_e32 v[110:111], 0
	v_mov_b64_e32 v[120:121], 0
	v_mov_b64_e32 v[122:123], 0
	v_mov_b64_e32 v[124:125], 0
	v_mov_b64_e32 v[126:127], 0
	v_mov_b64_e32 v[136:137], 0
	v_mov_b64_e32 v[138:139], 0
	v_mov_b64_e32 v[140:141], 0
	v_mov_b64_e32 v[142:143], 0
	s_mov_b64 s[82:83], 0x10000
	s_mov_b64 s[84:85], 0x10080
	s_mov_b64 s[86:87], 0x200000
	s_mov_b64 s[88:89], 0x100000
	s_mov_b64 s[92:93], 0x8000
	s_mov_b64 s[94:95], 0x18000
	s_mov_b64 s[96:97], 0x300000
	s_mov_b64 s[70:71], 0x8080
	s_mov_b64 s[68:69], 0x100080
	s_mov_b64 s[28:29], 0x18080
	s_cmp_eq_u32 s101, 2
	s_cselect_b32 s101, 0, s101
	s_setprio 0
	v_add_u32_e32 v255, 0x10000, v183

; #define G_WAIT_V(n) asm volatile("s_waitcnt vmcnt(" #n ")" ::: "memory")
; #define G_BAR __builtin_amdgcn_s_barrier()
;     ...
;     G_WAIT_V(0);
;     if (wr == 0) G_BAR;
;     G_BAR;
.Ldbj_SSM2_pe:
	s_setprio 0
	s_mov_b32 s101, 0
	s_waitcnt vmcnt(0)
	s_cmpk_gt_u32 s61, 0xff
	s_cbranch_scc1 .LBB0_746
	s_barrier

; #define G_STAGE(bufoff, gbase, o0, h64) do { \
;         __builtin_amdgcn_global_load_lds((const unsigned*)((const char*)(gbase) + (o0)), (LAS unsigned*)(lds + (bufoff) + ldsw), 16, 0, 0); \
;         __builtin_amdgcn_global_load_lds((const unsigned*)((const char*)(gbase) + (h64) + (o0)), (LAS unsigned*)(lds + (bufoff) + ldsw + 8192), 16, 0, 0); } while (0)
; #define G_LDA(dst, b, h) do { _Pragma("unroll") for (int m = 0; m < 4; ++m) _Pragma("unroll") for (int k = 0; k < 2; ++k) dst[m][k] = *(const LAS bf16x8*)(lds + G_SA(b, h) + aoff + m * 2048 + k * 1024); } while (0)
; #define G_LDB(dst, b, h) do { _Pragma("unroll") for (int n = 0; n < 2; ++n) _Pragma("unroll") for (int k = 0; k < 2; ++k) dst[n][k] = *(const LAS bf16x8*)(lds + G_SB(b, h) + boff + n * 2048 + k * 1024); } while (0)
; #define G_SCHED __builtin_amdgcn_sched_barrier(0)
;     ...
;     for (;;) {
;         const bool has_next = sched_next<PH, SUB>(E.ws, E.layer, ui + 1, nxt, E.x);
;         if (!has_next) nxt = cur;
;         const char* nA = nxt.A; const char* nB = nxt.B;
; #pragma unroll 1
;         for (int t = 0; t < nt; t += 2) {
;             const bool last = (t == nt - 2);
;             const char* a1 = cA + (size_t)(t + 1) * ckA;
;             const char* a2 = last ? nA : cA + (size_t)(t + 2) * ckA; const char* b2 = last ? nB : cB + (size_t)(t + 2) * kB;
;             const char* a3 = a2 + ckA; const char* b3 = b2 + kB;
;             G_LDB(B0, 0, 0); G_SCHED; G_LDA(At, 0, 0); G_STAGE(G_SA(1, 1), a1 + chA, cA0, qA);
.LBB0_803:
	s_add_u32 s13, s18, 0x100
	s_addc_u32 s18, s19, 0
	s_add_u32 s2, s2, 0x800000
	s_addc_u32 s3, s3, 0
	s_mov_b32 s19, -2
	s_mov_b64 s[42:43], 0x20080
	s_mov_b64 s[50:51], 0x10000
	s_mov_b64 s[52:53], 0x30000
	s_mov_b64 s[54:55], 0x10080
	s_mov_b64 s[58:59], 0x30080
	s_mov_b64 s[62:63], 0x400000
	s_cmp_eq_u32 s101, 2
	s_cselect_b32 s101, 0, s101
	s_setprio 0
	v_add_u32_e32 v255, 0x10000, v196
	s_add_i32 s40, 0, 0x10000
	ds_read_b128 v[112:115], v255 offset:0
	ds_read_b128 v[124:127], v255 offset:1024
	ds_read_b128 v[136:139], v255 offset:2048
	ds_read_b128 v[148:151], v255 offset:3072
	s_cmp_eq_u32 s19, 4
	s_cselect_b32 s5, s15, s3
	s_cselect_b32 s4, s14, s2
	s_cselect_b32 s37, s17, s18
	s_cselect_b32 s36, s16, s13
	s_mov_b32 s38, 0xffc01000
	s_mov_b32 s39, -1
	s_add_u32 vcc_lo, s2, s38
	s_addc_u32 vcc_hi, s3, s39
	s_mov_b32 s38, 0xffc01800
	s_add_i32 m0, s24, 0xc000
	s_mov_b32 s39, -1
	ds_read_b128 v[152:155], v197
	ds_read_b128 v[156:159], v197 offset:1024
	ds_read_b128 v[160:163], v197 offset:2048
	ds_read_b128 v[172:175], v197 offset:3072
	ds_read_b128 v[176:179], v197 offset:4096
	ds_read_b128 v[180:183], v197 offset:5120
	ds_read_b128 v[198:201], v197 offset:6144
	ds_read_b128 v[202:205], v197 offset:7168
	global_load_lds_dwordx4 v166, vcc
	s_add_i32 m0, s24, 0xe000
	s_nop 0
	s_add_u32 vcc_lo, s2, s38
	s_addc_u32 vcc_hi, s3, s39
	global_load_lds_dwordx4 v166, vcc
	s_waitcnt lgkmcnt(8)
	s_cmp_eq_u32 s101, 1
	s_cbranch_scc1 .Ldb_GLU_skp
	s_barrier

; #define G_WAIT_V(n) asm volatile("s_waitcnt vmcnt(" #n ")" ::: "memory")
; #define G_BAR __builtin_amdgcn_s_barrier()
;     ...
;     G_WAIT_V(0);
;     if (wr == 0) G_BAR;
;     G_BAR;
.Ldbj_GLU_pe:
	s_setprio 0
	s_mov_b32 s101, 0
	s_waitcnt vmcnt(0)
	s_cmpk_gt_u32 s20, 0xff
	s_cbranch_scc1 .LBB0_808
	s_barrier

; #define G_STAGE(bufoff, gbase, o0, h64) do { \
;         __builtin_amdgcn_global_load_lds((const unsigned*)((const char*)(gbase) + (o0)), (LAS unsigned*)(lds + (bufoff) + ldsw), 16, 0, 0); \
;         __builtin_amdgcn_global_load_lds((const unsigned*)((const char*)(gbase) + (h64) + (o0)), (LAS unsigned*)(lds + (bufoff) + ldsw + 8192), 16, 0, 0); } while (0)
; #define G_LDA(dst, b, h) do { _Pragma("unroll") for (int m = 0; m < 4; ++m) _Pragma("unroll") for (int k = 0; k < 2; ++k) dst[m][k] = *(const LAS bf16x8*)(lds + G_SA(b, h) + aoff + m * 2048 + k * 1024); } while (0)
; #define G_LDB(dst, b, h) do { _Pragma("unroll") for (int n = 0; n < 2; ++n) _Pragma("unroll") for (int k = 0; k < 2; ++k) dst[n][k] = *(const LAS bf16x8*)(lds + G_SB(b, h) + boff + n * 2048 + k * 1024); } while (0)
; #define G_SCHED __builtin_amdgcn_sched_barrier(0)
;     ...
;     for (;;) {
;         const bool has_next = sched_next<PH, SUB>(E.ws, E.layer, ui + 1, nxt, E.x);
;         if (!has_next) nxt = cur;
;         const char* nA = nxt.A; const char* nB = nxt.B;
; #pragma unroll 1
;         for (int t = 0; t < nt; t += 2) {
;             const bool last = (t == nt - 2);
;             const char* a1 = cA + (size_t)(t + 1) * ckA;
;             const char* a2 = last ? nA : cA + (size_t)(t + 2) * ckA; const char* b2 = last ? nB : cB + (size_t)(t + 2) * kB;
;             const char* a3 = a2 + ckA; const char* b3 = b2 + kB;
;             G_LDB(B0, 0, 0); G_SCHED; G_LDA(At, 0, 0); G_STAGE(G_SA(1, 1), a1 + chA, cA0, qA);
.LBB0_871:
	s_add_u32 s2, s2, 0xb0080
	s_addc_u32 s3, s3, 0
	s_add_u32 s37, s12, 0x100
	s_addc_u32 s38, s13, 0
	s_mov_b32 s39, -2
	s_mov_b64 s[42:43], 0x20080
	s_mov_b64 s[50:51], 0x10000
	s_mov_b64 s[52:53], 0x30000
	s_mov_b64 s[54:55], 0x10080
	s_mov_b64 s[58:59], 0x30080
	s_cmp_eq_u32 s101, 2
	s_cselect_b32 s101, 0, s101
	s_setprio 0
	v_add_u32_e32 v239, 0x10000, v159
	s_add_u32 s4, s2, 0xfff50080
	s_addc_u32 s5, s3, -1
	s_add_i32 s40, 0, 0x10000
	ds_read_b128 v[144:147], v239 offset:0
	ds_read_b128 v[148:151], v239 offset:1024
	ds_read_b128 v[136:139], v239 offset:2048
	ds_read_b128 v[140:143], v239 offset:3072
	s_cmp_eq_u32 s39, 4
	s_cselect_b32 s13, s9, s5
	s_cselect_b32 s12, s8, s4
	s_cselect_b32 s15, s11, s38
	s_cselect_b32 s14, s10, s37
	s_add_i32 m0, s22, 0xc000
	ds_read_b128 v[160:163], v236
	ds_read_b128 v[164:167], v236 offset:1024
	ds_read_b128 v[176:179], v236 offset:2048
	ds_read_b128 v[180:183], v236 offset:3072
	ds_read_b128 v[196:199], v236 offset:4096
	ds_read_b128 v[200:203], v236 offset:5120
	ds_read_b128 v[204:207], v236 offset:6144
	ds_read_b128 v[208:211], v236 offset:7168
	global_load_lds_dwordx4 v152, s[2:3]
	s_add_i32 m0, s22, 0xe000
	s_nop 0
	s_add_u32 vcc_lo, s2, s86
	s_addc_u32 vcc_hi, s3, s87
	global_load_lds_dwordx4 v152, vcc
	s_waitcnt lgkmcnt(8)
	s_cmp_eq_u32 s101, 1
	s_cbranch_scc1 .Ldb_MG0_skp
	s_barrier

; #define G_WAIT_V(n) asm volatile("s_waitcnt vmcnt(" #n ")" ::: "memory")
; #define G_BAR __builtin_amdgcn_s_barrier()
;     ...
;     G_WAIT_V(0);
;     if (wr == 0) G_BAR;
;     G_BAR;
.Ldbj_MG0_pe:
	s_setprio 0
	s_mov_b32 s101, 0
	s_waitcnt vmcnt(0)
	s_cmpk_gt_u32 s16, 0xff
	s_cbranch_scc1 .LBB0_876
	s_barrier

;     ...
;     for (;;) {
;         const bool has_next = sched_next<PH, SUB>(E.ws, E.layer, ui + 1, nxt, E.x);
;         if (!has_next) nxt = cur;
;         const char* nA = nxt.A; const char* nB = nxt.B;
.LBB0_889:
	s_add_u32 s6, s6, 0xb0080
	s_addc_u32 s7, s7, 0
	s_add_u32 s8, s18, 0x100
	s_addc_u32 s9, s19, 0
	s_mov_b32 s18, -2
	s_mov_b64 s[50:51], 0x20080
	s_mov_b64 s[52:53], 0x30000
	s_mov_b64 s[54:55], 0x10080
	s_mov_b64 s[58:59], 0x30080
	s_cmp_eq_u32 s101, 2
	s_cselect_b32 s101, 0, s101
	s_setprio 0
	v_add_u32_e32 v239, 0x10000, v175

; #define G_STAGE(bufoff, gbase, o0, h64) do { \
;         __builtin_amdgcn_global_load_lds((const unsigned*)((const char*)(gbase) + (o0)), (LAS unsigned*)(lds + (bufoff) + ldsw), 16, 0, 0); \
;         __builtin_amdgcn_global_load_lds((const unsigned*)((const char*)(gbase) + (h64) + (o0)), (LAS unsigned*)(lds + (bufoff) + ldsw + 8192), 16, 0, 0); } while (0)
; #define G_LDA(dst, b, h) do { _Pragma("unroll") for (int m = 0; m < 4; ++m) _Pragma("unroll") for (int k = 0; k < 2; ++k) dst[m][k] = *(const LAS bf16x8*)(lds + G_SA(b, h) + aoff + m * 2048 + k * 1024); } while (0)
; #define G_LDB(dst, b, h) do { _Pragma("unroll") for (int n = 0; n < 2; ++n) _Pragma("unroll") for (int k = 0; k < 2; ++k) dst[n][k] = *(const LAS bf16x8*)(lds + G_SB(b, h) + boff + n * 2048 + k * 1024); } while (0)
; #define G_SCHED __builtin_amdgcn_sched_barrier(0)
;     ...
;     for (;;) {
;         const bool has_next = sched_next<PH, SUB>(E.ws, E.layer, ui + 1, nxt, E.x);
;         if (!has_next) nxt = cur;
;         const char* nA = nxt.A; const char* nB = nxt.B;
; #pragma unroll 1
;         for (int t = 0; t < nt; t += 2) {
;             const bool last = (t == nt - 2);
;             const char* a1 = cA + (size_t)(t + 1) * ckA;
;             const char* a2 = last ? nA : cA + (size_t)(t + 2) * ckA; const char* b2 = last ? nB : cB + (size_t)(t + 2) * kB;
;             const char* a3 = a2 + ckA; const char* b3 = b2 + kB;
;             G_LDB(B0, 0, 0); G_SCHED; G_LDA(At, 0, 0); G_STAGE(G_SA(1, 1), a1 + chA, cA0, qA);
.LBB0_1036:
	s_add_u32 s2, s2, 0x40080
	s_addc_u32 s3, s3, 0
	s_add_u32 s6, s6, 0x100
	s_waitcnt lgkmcnt(0)
	s_addc_u32 s7, s7, 0
	s_mov_b32 s15, -2
	s_mov_b64 s[42:43], 0x40000
	s_mov_b64 s[50:51], 0x60000
	s_mov_b64 s[52:53], 0x20080
	s_mov_b64 s[54:55], 0x40080
	s_mov_b64 s[58:59], 0x60080
	s_cmp_eq_u32 s101, 2
	s_cselect_b32 s101, 0, s101
	s_setprio 0
	v_add_u32_e32 v255, 0x10000, v181
	s_add_u32 s4, s2, 0xfffc0080
	s_addc_u32 s5, s3, -1
	s_add_i32 s33, 0, 0x10000
	ds_read_b128 v[136:139], v255 offset:0
	ds_read_b128 v[140:143], v255 offset:1024
	ds_read_b128 v[144:147], v255 offset:2048
	ds_read_b128 v[148:151], v255 offset:3072
	s_cmp_eq_u32 s15, 12
	s_cselect_b32 s5, s17, s5
	s_cselect_b32 s4, s16, s4
	s_cselect_b32 s21, s19, s7
	s_cselect_b32 s20, s18, s6
	s_add_i32 m0, s24, 0xc000
	ds_read_b128 v[152:155], v182
	ds_read_b128 v[156:159], v182 offset:1024
	ds_read_b128 v[160:163], v182 offset:2048
	ds_read_b128 v[172:175], v182 offset:3072
	ds_read_b128 v[176:179], v182 offset:4096
	ds_read_b128 v[196:199], v182 offset:5120
	ds_read_b128 v[200:203], v182 offset:6144
	ds_read_b128 v[204:207], v182 offset:7168
	global_load_lds_dwordx4 v166, s[2:3]
	s_add_i32 m0, s24, 0xe000
	s_nop 0
	s_add_u32 vcc_lo, s2, s0
	s_addc_u32 vcc_hi, s3, s1
	global_load_lds_dwordx4 v166, vcc
	s_waitcnt lgkmcnt(8)
	s_cmp_eq_u32 s101, 1
	s_cbranch_scc1 .Ldb_WOUT_skp
	s_barrier

; #define G_WAIT_V(n) asm volatile("s_waitcnt vmcnt(" #n ")" ::: "memory")
; #define G_BAR __builtin_amdgcn_s_barrier()
;     ...
;     G_WAIT_V(0);
;     if (wr == 0) G_BAR;
;     G_BAR;
.Ldbj_WOUT_pe:
	s_setprio 0
	s_mov_b32 s101, 0
	s_waitcnt vmcnt(0)
	s_cmpk_gt_u32 s22, 0xff
	s_cbranch_scc1 .LBB0_1056
	s_barrier

; #define G_STAGE(bufoff, gbase, o0, h64) do { \
;         __builtin_amdgcn_global_load_lds((const unsigned*)((const char*)(gbase) + (o0)), (LAS unsigned*)(lds + (bufoff) + ldsw), 16, 0, 0); \
;         __builtin_amdgcn_global_load_lds((const unsigned*)((const char*)(gbase) + (h64) + (o0)), (LAS unsigned*)(lds + (bufoff) + ldsw + 8192), 16, 0, 0); } while (0)
; #define G_LDA(dst, b, h) do { _Pragma("unroll") for (int m = 0; m < 4; ++m) _Pragma("unroll") for (int k = 0; k < 2; ++k) dst[m][k] = *(const LAS bf16x8*)(lds + G_SA(b, h) + aoff + m * 2048 + k * 1024); } while (0)
; #define G_LDB(dst, b, h) do { _Pragma("unroll") for (int n = 0; n < 2; ++n) _Pragma("unroll") for (int k = 0; k < 2; ++k) dst[n][k] = *(const LAS bf16x8*)(lds + G_SB(b, h) + boff + n * 2048 + k * 1024); } while (0)
; #define G_SCHED __builtin_amdgcn_sched_barrier(0)
;     ...
;     for (;;) {
;         const bool has_next = sched_next<PH, SUB>(E.ws, E.layer, ui + 1, nxt, E.x);
;         if (!has_next) nxt = cur;
;         const char* nA = nxt.A; const char* nB = nxt.B;
; #pragma unroll 1
;         for (int t = 0; t < nt; t += 2) {
;             const bool last = (t == nt - 2);
;             const char* a1 = cA + (size_t)(t + 1) * ckA;
;             const char* a2 = last ? nA : cA + (size_t)(t + 2) * ckA; const char* b2 = last ? nB : cB + (size_t)(t + 2) * kB;
;             const char* a3 = a2 + ckA; const char* b3 = b2 + kB;
;             G_LDB(B0, 0, 0); G_SCHED; G_LDA(At, 0, 0); G_STAGE(G_SA(1, 1), a1 + chA, cA0, qA);
.LBB0_1119:
	s_add_u32 s2, s16, 0x40080
	s_addc_u32 s3, s17, 0
	s_add_u32 s16, s18, 0x100
	s_addc_u32 s17, s19, 0
	s_mov_b32 s18, -2
	s_mov_b64 s[42:43], 0x40000
	s_mov_b64 s[50:51], 0x60000
	s_mov_b64 s[52:53], 0x20080
	s_mov_b64 s[54:55], 0x40080
	s_mov_b64 s[58:59], 0x60080
	s_cmp_eq_u32 s101, 2
	s_cselect_b32 s101, 0, s101
	s_setprio 0
	v_add_u32_e32 v235, 0x10000, v149
	s_add_u32 s4, s2, 0xfffc0080
	s_addc_u32 s5, s3, -1
	s_add_i32 s19, 0, 0x10000
	ds_read_b128 v[140:143], v235 offset:0
	ds_read_b128 v[144:147], v235 offset:1024
	ds_read_b128 v[152:155], v235 offset:2048
	ds_read_b128 v[156:159], v235 offset:3072
	s_cmp_eq_u32 s18, 12
	s_cselect_b32 s5, s13, s5
	s_cselect_b32 s4, s12, s4
	s_cselect_b32 s41, s15, s17
	s_cselect_b32 s40, s14, s16
	s_add_i32 m0, s26, 0xc000
	ds_read_b128 v[160:163], v150
	ds_read_b128 v[164:167], v150 offset:1024
	ds_read_b128 v[172:175], v150 offset:2048
	ds_read_b128 v[176:179], v150 offset:3072
	ds_read_b128 v[180:183], v150 offset:4096
	ds_read_b128 v[196:199], v150 offset:5120
	ds_read_b128 v[200:203], v150 offset:6144
	ds_read_b128 v[204:207], v150 offset:7168
	global_load_lds_dwordx4 v138, s[2:3]
	s_add_i32 m0, s26, 0xe000
	s_nop 0
	s_add_u32 vcc_lo, s2, s0
	s_addc_u32 vcc_hi, s3, s1
	global_load_lds_dwordx4 v138, vcc
	s_waitcnt lgkmcnt(8)
	s_cmp_eq_u32 s101, 1
	s_cbranch_scc1 .Ldb_FFI_skp
	s_barrier

; #define G_STAGE(bufoff, gbase, o0, h64) do { \
;         __builtin_amdgcn_global_load_lds((const unsigned*)((const char*)(gbase) + (o0)), (LAS unsigned*)(lds + (bufoff) + ldsw), 16, 0, 0); \
;         __builtin_amdgcn_global_load_lds((const unsigned*)((const char*)(gbase) + (h64) + (o0)), (LAS unsigned*)(lds + (bufoff) + ldsw + 8192), 16, 0, 0); } while (0)
; #define G_LDA(dst, b, h) do { _Pragma("unroll") for (int m = 0; m < 4; ++m) _Pragma("unroll") for (int k = 0; k < 2; ++k) dst[m][k] = *(const LAS bf16x8*)(lds + G_SA(b, h) + aoff + m * 2048 + k * 1024); } while (0)
; #define G_LDB(dst, b, h) do { _Pragma("unroll") for (int n = 0; n < 2; ++n) _Pragma("unroll") for (int k = 0; k < 2; ++k) dst[n][k] = *(const LAS bf16x8*)(lds + G_SB(b, h) + boff + n * 2048 + k * 1024); } while (0)
; #define G_SCHED __builtin_amdgcn_sched_barrier(0)
;     ...
;     for (;;) {
;         const bool has_next = sched_next<PH, SUB>(E.ws, E.layer, ui + 1, nxt, E.x);
;         if (!has_next) nxt = cur;
;         const char* nA = nxt.A; const char* nB = nxt.B;
; #pragma unroll 1
;         for (int t = 0; t < nt; t += 2) {
;             const bool last = (t == nt - 2);
;             const char* a1 = cA + (size_t)(t + 1) * ckA;
;             const char* a2 = last ? nA : cA + (size_t)(t + 2) * ckA; const char* b2 = last ? nB : cB + (size_t)(t + 2) * kB;
;             const char* a3 = a2 + ckA; const char* b3 = b2 + kB;
;             G_LDB(B0, 0, 0); G_SCHED; G_LDA(At, 0, 0); G_STAGE(G_SA(1, 1), a1 + chA, cA0, qA);
.LBB0_1184:
	s_add_u32 s2, s2, 0xb0080
	s_addc_u32 s3, s3, 0
	s_add_u32 s6, s6, 0x100
	s_waitcnt lgkmcnt(0)
	s_addc_u32 s7, s7, 0
	s_mov_b32 s21, -2
	s_mov_b64 s[52:53], 0xb0080
	s_mov_b64 s[54:55], 0x108080
	s_cmp_eq_u32 s101, 2
	s_cselect_b32 s101, 0, s101
	s_setprio 0
	v_add_u32_e32 v255, 0x10000, v185
	s_add_u32 s4, s2, 0xfff50080
	s_addc_u32 s5, s3, -1
	s_add_i32 s33, 0, 0x10000
	ds_read_b128 v[136:139], v255 offset:0
	ds_read_b128 v[140:143], v255 offset:1024
	ds_read_b128 v[144:147], v255 offset:2048
	ds_read_b128 v[148:151], v255 offset:3072
	s_cmp_eq_u32 s21, 40
	s_cselect_b32 s5, s17, s5
	s_cselect_b32 s4, s16, s4
	s_cselect_b32 s23, s19, s7
	s_cselect_b32 s22, s18, s6
	s_add_i32 m0, s26, 0xc000
	ds_read_b128 v[152:155], v195
	ds_read_b128 v[156:159], v195 offset:1024
	ds_read_b128 v[160:163], v195 offset:2048
	ds_read_b128 v[164:167], v195 offset:3072
	ds_read_b128 v[176:179], v195 offset:4096
	ds_read_b128 v[180:183], v195 offset:5120
	ds_read_b128 v[196:199], v195 offset:6144
	ds_read_b128 v[200:203], v195 offset:7168
	global_load_lds_dwordx4 v174, s[2:3]
	s_add_i32 m0, s26, 0xe000
	s_nop 0
	s_add_u32 vcc_lo, s2, s86
	s_addc_u32 vcc_hi, s3, s87
	global_load_lds_dwordx4 v174, vcc
	s_waitcnt lgkmcnt(8)
	s_cmp_eq_u32 s101, 1
	s_cbranch_scc1 .Ldb_FFO_skp
	s_barrier

; #define G_STAGE(bufoff, gbase, o0, h64) do { \
;         __builtin_amdgcn_global_load_lds((const unsigned*)((const char*)(gbase) + (o0)), (LAS unsigned*)(lds + (bufoff) + ldsw), 16, 0, 0); \
;         __builtin_amdgcn_global_load_lds((const unsigned*)((const char*)(gbase) + (h64) + (o0)), (LAS unsigned*)(lds + (bufoff) + ldsw + 8192), 16, 0, 0); } while (0)
; #define G_LDA(dst, b, h) do { _Pragma("unroll") for (int m = 0; m < 4; ++m) _Pragma("unroll") for (int k = 0; k < 2; ++k) dst[m][k] = *(const LAS bf16x8*)(lds + G_SA(b, h) + aoff + m * 2048 + k * 1024); } while (0)
; #define G_LDB(dst, b, h) do { _Pragma("unroll") for (int n = 0; n < 2; ++n) _Pragma("unroll") for (int k = 0; k < 2; ++k) dst[n][k] = *(const LAS bf16x8*)(lds + G_SB(b, h) + boff + n * 2048 + k * 1024); } while (0)
; #define G_SCHED __builtin_amdgcn_sched_barrier(0)
;     ...
;     for (;;) {
;         const bool has_next = sched_next<PH, SUB>(E.ws, E.layer, ui + 1, nxt, E.x);
;         if (!has_next) nxt = cur;
;         const char* nA = nxt.A; const char* nB = nxt.B;
; #pragma unroll 1
;         for (int t = 0; t < nt; t += 2) {
;             const bool last = (t == nt - 2);
;             const char* a1 = cA + (size_t)(t + 1) * ckA;
;             const char* a2 = last ? nA : cA + (size_t)(t + 2) * ckA; const char* b2 = last ? nB : cB + (size_t)(t + 2) * kB;
;             const char* a3 = a2 + ckA; const char* b3 = b2 + kB;
;             G_LDB(B0, 0, 0); G_SCHED; G_LDA(At, 0, 0); G_STAGE(G_SA(1, 1), a1 + chA, cA0, qA);
.LBB0_1259:
	s_mov_b64 s[18:19], 0
	s_mov_b64 s[14:15], -1
	s_mov_b64 s[16:17], 0
	s_mov_b64 s[58:59], 0x10000
	s_cmp_eq_u32 s101, 2
	s_cselect_b32 s101, 0, s101
	s_setprio 0
	v_add_u32_e32 v255, 0x10000, v137
	s_add_u32 s22, s10, s18
	s_addc_u32 s23, s11, s19
	s_add_u32 s20, s22, 0x100
	s_addc_u32 s21, s23, 0
	s_and_b64 s[4:5], s[16:17], exec
	s_cselect_b32 s20, s6, s20
	s_cselect_b32 s21, s7, s21
	s_add_u32 s4, s12, s18
	s_addc_u32 s5, s13, s19
	s_add_u32 s18, s4, 0x100
	s_addc_u32 s19, s5, 0
	s_add_i32 s44, 0, 0x10000
	ds_read_b128 v[140:143], v255 offset:0
	ds_read_b128 v[144:147], v255 offset:1024
	ds_read_b128 v[148:151], v255 offset:2048
	ds_read_b128 v[152:155], v255 offset:3072
	s_and_b64 s[4:5], s[16:17], exec
	s_cselect_b32 s16, s8, s18
	s_cselect_b32 s17, s9, s19
	s_add_i32 s5, 0, 0x14000
	s_add_i32 s43, 0, 0x18000
	s_add_i32 s18, 0, 0x1c000
	s_add_i32 s45, s44, s25
	s_add_i32 s51, s5, s25
	s_add_i32 s19, s43, s25
	s_add_i32 s53, s18, s25
	s_mov_b64 s[64:65], 0x8000
	s_mov_b64 s[62:63], 0x10080
	s_add_i32 m0, s31, 0xc000
	s_add_i32 s4, s31, 0xe000
	s_add_i32 s54, s45, 0x2000
	s_add_i32 s50, s51, 0x2000
	s_add_i32 s44, s19, 0x2000
	s_add_i32 s52, s53, 0x2000
	ds_read_b128 v[156:159], v138
	ds_read_b128 v[160:163], v138 offset:1024
	ds_read_b128 v[164:167], v138 offset:2048
	ds_read_b128 v[172:175], v138 offset:3072
	ds_read_b128 v[176:179], v138 offset:4096
	ds_read_b128 v[180:183], v138 offset:5120
	ds_read_b128 v[196:199], v138 offset:6144
	ds_read_b128 v[200:203], v138 offset:7168
	s_add_u32 vcc_lo, s22, s62
	s_addc_u32 vcc_hi, s23, s63
	global_load_lds_dwordx4 v2, vcc
	s_mov_b32 m0, s4
	s_nop 0
	s_add_u32 vcc_lo, s22, s68
	s_addc_u32 vcc_hi, s23, s69
	global_load_lds_dwordx4 v2, vcc
	s_waitcnt lgkmcnt(8)
	s_cmp_eq_u32 s101, 1
	s_cbranch_scc1 .Ldb_PLE0_skp
	s_barrier

; #define G_STAGE(bufoff, gbase, o0, h64) do { \
;         __builtin_amdgcn_global_load_lds((const unsigned*)((const char*)(gbase) + (o0)), (LAS unsigned*)(lds + (bufoff) + ldsw), 16, 0, 0); \
;         __builtin_amdgcn_global_load_lds((const unsigned*)((const char*)(gbase) + (h64) + (o0)), (LAS unsigned*)(lds + (bufoff) + ldsw + 8192), 16, 0, 0); } while (0)
; #define G_LDA(dst, b, h) do { _Pragma("unroll") for (int m = 0; m < 4; ++m) _Pragma("unroll") for (int k = 0; k < 2; ++k) dst[m][k] = *(const LAS bf16x8*)(lds + G_SA(b, h) + aoff + m * 2048 + k * 1024); } while (0)
; #define G_LDB(dst, b, h) do { _Pragma("unroll") for (int n = 0; n < 2; ++n) _Pragma("unroll") for (int k = 0; k < 2; ++k) dst[n][k] = *(const LAS bf16x8*)(lds + G_SB(b, h) + boff + n * 2048 + k * 1024); } while (0)
; #define G_SCHED __builtin_amdgcn_sched_barrier(0)
;     ...
;     for (;;) {
;         const bool has_next = sched_next<PH, SUB>(E.ws, E.layer, ui + 1, nxt, E.x);
;         if (!has_next) nxt = cur;
;         const char* nA = nxt.A; const char* nB = nxt.B;
; #pragma unroll 1
;         for (int t = 0; t < nt; t += 2) {
;             const bool last = (t == nt - 2);
;             const char* a1 = cA + (size_t)(t + 1) * ckA;
;             const char* a2 = last ? nA : cA + (size_t)(t + 2) * ckA; const char* b2 = last ? nB : cB + (size_t)(t + 2) * kB;
;             const char* a3 = a2 + ckA; const char* b3 = b2 + kB;
;             G_LDB(B0, 0, 0); G_SCHED; G_LDA(At, 0, 0); G_STAGE(G_SA(1, 1), a1 + chA, cA0, qA);
.LBB0_1282:
	s_add_u32 s2, s24, 0x40080
	s_addc_u32 s3, s25, 0
	s_add_u32 s22, s22, 0x100
	s_waitcnt lgkmcnt(0)
	s_addc_u32 s23, s23, 0
	s_mov_b32 s24, -2
	s_mov_b64 s[54:55], 0x40000
	s_mov_b64 s[58:59], 0x60000
	s_mov_b64 s[62:63], 0x20080
	s_mov_b64 s[64:65], 0x40080
	s_mov_b64 s[66:67], 0x60080
	s_cmp_eq_u32 s101, 2
	s_cselect_b32 s101, 0, s101
	s_setprio 0
	v_add_u32_e32 v255, 0x10000, v181
	s_add_u32 s4, s2, 0xfffc0080
	s_addc_u32 s5, s3, -1
	s_add_i32 s25, 0, 0x10000
	ds_read_b128 v[136:139], v255 offset:0
	ds_read_b128 v[140:143], v255 offset:1024
	ds_read_b128 v[144:147], v255 offset:2048
	ds_read_b128 v[148:151], v255 offset:3072
	s_cmp_eq_u32 s24, 12
	s_cselect_b32 s5, s19, s5
	s_cselect_b32 s4, s18, s4
	s_cselect_b32 s41, s21, s23
	s_cselect_b32 s40, s20, s22
	s_add_i32 m0, s29, 0xc000
	ds_read_b128 v[152:155], v182
	ds_read_b128 v[160:163], v182 offset:1024
	ds_read_b128 v[164:167], v182 offset:2048
	ds_read_b128 v[172:175], v182 offset:3072
	ds_read_b128 v[176:179], v182 offset:4096
	ds_read_b128 v[196:199], v182 offset:5120
	ds_read_b128 v[200:203], v182 offset:6144
	ds_read_b128 v[204:207], v182 offset:7168
	global_load_lds_dwordx4 v158, s[2:3]
	s_add_i32 m0, s29, 0xe000
	s_nop 0
	s_add_u32 vcc_lo, s2, s0
	s_addc_u32 vcc_hi, s3, s1
	global_load_lds_dwordx4 v158, vcc
	s_waitcnt lgkmcnt(8)
	s_cmp_eq_u32 s101, 1
	s_cbranch_scc1 .Ldb_PLE1_skp
	s_barrier

; #define G_WAIT_V(n) asm volatile("s_waitcnt vmcnt(" #n ")" ::: "memory")
; #define G_BAR __builtin_amdgcn_s_barrier()
;     ...
;     G_WAIT_V(0);
;     if (wr == 0) G_BAR;
;     G_BAR;
.Ldbj_PLE1_pe:
	s_setprio 0
	s_mov_b32 s101, 0
	s_waitcnt vmcnt(0)
	s_cmpk_gt_u32 s26, 0xff
	s_cbranch_scc1 .LBB0_1302
	s_barrier
